# grid barrier: the 25th of 32 arrivers in each XCD issues an early L2 write-back (buffer_wbl2) so the leader's final write-back has less dirty data
# baseline (speedup 1.0000x reference)
; __device__ __forceinline__ unsigned xb_ld(unsigned* p)              { return __hip_atomic_load(p, __ATOMIC_RELAXED, __HIP_MEMORY_SCOPE_AGENT); }
; __device__ __forceinline__ unsigned xb_add(unsigned* p, unsigned v) { return __hip_atomic_fetch_add(p, v, __ATOMIC_RELAXED, __HIP_MEMORY_SCOPE_AGENT); }
; #define XB_SPIN(cond, bar) do { unsigned _sp = 0; while (cond) { __builtin_amdgcn_s_sleep(1); \
;     if ((++_sp & 255u) == 0u) { if (xb_ld(&(bar)[XB_TMO])) break; if (_sp > XB_SPIN_CAP) { atomicAdd(&(bar)[XB_TMO], 1u); break; } } } } while (0)
; __device__ __forceinline__ void xcd_barrier(const XcdBarrier& b) {
;     ...
;         const unsigned old = xb_add(&bar[XB_XSUB(b.x)], 1u);
;         const unsigned gen = old / nloc;
;         if (old + 1u == (gen + 1u) * nloc) {
;             __builtin_amdgcn_fence(__ATOMIC_RELEASE, "agent");
;             asm volatile("s_waitcnt vmcnt(0)" ::: "memory");
;             const unsigned og = xb_add(&bar[XB_TOP], 1u);
;             const unsigned tg = og / nx;
;             if (og + 1u == (tg + 1u) * nx) xb_add(&bar[XB_TOPGEN], 1u);
;             else XB_SPIN(xb_ld(&bar[XB_TOPGEN]) == tg, bar);
;             __builtin_amdgcn_fence(__ATOMIC_ACQUIRE, "agent");
;             xb_add(&bar[XB_XGEN(b.x)], 1u);
;             asm volatile("s_waitcnt vmcnt(0)" ::: "memory");
;         } else {
;             XB_SPIN(xb_ld(&bar[XB_XGEN(b.x)]) == gen, bar);
;             __builtin_amdgcn_fence(__ATOMIC_ACQUIRE, "agent");
;             asm volatile("s_waitcnt vmcnt(0)" ::: "memory");
.LBB0_144:
	s_or_b64 exec, exec, s[8:9]
	v_cvt_f32_u32_e32 v5, v3
	s_waitcnt vmcnt(0)
	v_readfirstlane_b32 s3, v4
	v_sub_u32_e32 v4, 0, v3
	v_rcp_iflag_f32_e32 v5, v5
	v_add_u32_e32 v6, s3, v2
	v_mul_f32_e32 v5, 0x4f7ffffe, v5
	v_cvt_u32_f32_e32 v5, v5
	v_mul_lo_u32 v2, v4, v5
	v_mul_hi_u32 v2, v5, v2
	v_add_u32_e32 v2, v5, v2
	v_mul_hi_u32 v2, v6, v2
	v_mul_lo_u32 v4, v2, v3
	v_sub_u32_e32 v4, v6, v4
	v_add_u32_e32 v5, 1, v2
	v_cmp_ge_u32_e32 vcc, v4, v3
	s_nop 1
	v_cndmask_b32_e32 v2, v2, v5, vcc
	v_sub_u32_e32 v5, v4, v3
	v_cndmask_b32_e32 v4, v4, v5, vcc
	v_add_u32_e32 v5, 1, v2
	v_cmp_ge_u32_e32 vcc, v4, v3
	v_add_u32_e32 v4, 1, v6
	s_nop 0
	v_cndmask_b32_e32 v2, v2, v5, vcc
	v_mul_lo_u32 v5, v3, v2
	v_add_u32_e32 v3, v5, v3
	v_cmp_ne_u32_e32 vcc, v4, v3
	s_and_saveexec_b64 s[6:7], vcc
	s_xor_b64 s[6:7], exec, s[6:7]
	s_cbranch_execz .LBB0_158
	s_waitcnt lgkmcnt(0)
	v_sub_u32_e32 v4, v6, v5
	v_cmp_eq_u32_e32 vcc, 24, v4
	s_cbranch_vccz .Lnf_0
	buffer_wbl2 sc1
.Lnf_0:
	v_mov_b32_e32 v1, 0x3500
	global_load_dword v1, v1, s[30:31] sc1
	s_add_u32 s10, s30, 0x3500
	s_addc_u32 s11, s31, 0
	s_waitcnt vmcnt(0)
	v_cmp_eq_u32_e32 vcc, v1, v2
	s_and_saveexec_b64 s[8:9], vcc
	s_cbranch_execz .LBB0_157
	s_mov_b32 s3, 1
	s_mov_b64 s[12:13], 0
	v_mov_b32_e32 v1, 0
	s_branch .LBB0_148

; __device__ __forceinline__ unsigned xb_ld(unsigned* p)              { return __hip_atomic_load(p, __ATOMIC_RELAXED, __HIP_MEMORY_SCOPE_AGENT); }
; __device__ __forceinline__ unsigned xb_add(unsigned* p, unsigned v) { return __hip_atomic_fetch_add(p, v, __ATOMIC_RELAXED, __HIP_MEMORY_SCOPE_AGENT); }
; #define XB_SPIN(cond, bar) do { unsigned _sp = 0; while (cond) { __builtin_amdgcn_s_sleep(1); \
;     if ((++_sp & 255u) == 0u) { if (xb_ld(&(bar)[XB_TMO])) break; if (_sp > XB_SPIN_CAP) { atomicAdd(&(bar)[XB_TMO], 1u); break; } } } } while (0)
; __device__ __forceinline__ void xcd_barrier(const XcdBarrier& b) {
;     ...
;         const unsigned old = xb_add(&bar[XB_XSUB(b.x)], 1u);
;         const unsigned gen = old / nloc;
;         if (old + 1u == (gen + 1u) * nloc) {
;             __builtin_amdgcn_fence(__ATOMIC_RELEASE, "agent");
;             asm volatile("s_waitcnt vmcnt(0)" ::: "memory");
;             const unsigned og = xb_add(&bar[XB_TOP], 1u);
;             const unsigned tg = og / nx;
;             if (og + 1u == (tg + 1u) * nx) xb_add(&bar[XB_TOPGEN], 1u);
;             else XB_SPIN(xb_ld(&bar[XB_TOPGEN]) == tg, bar);
;             __builtin_amdgcn_fence(__ATOMIC_ACQUIRE, "agent");
;             xb_add(&bar[XB_XGEN(b.x)], 1u);
;             asm volatile("s_waitcnt vmcnt(0)" ::: "memory");
;         } else {
;             XB_SPIN(xb_ld(&bar[XB_XGEN(b.x)]) == gen, bar);
;             __builtin_amdgcn_fence(__ATOMIC_ACQUIRE, "agent");
;             asm volatile("s_waitcnt vmcnt(0)" ::: "memory");
.LBB0_247:
	s_or_b64 exec, exec, s[8:9]
	v_cvt_f32_u32_e32 v5, v3
	s_waitcnt vmcnt(0)
	v_readfirstlane_b32 s6, v4
	v_sub_u32_e32 v4, 0, v3
	v_rcp_iflag_f32_e32 v5, v5
	v_add_u32_e32 v6, s6, v2
	v_mul_f32_e32 v5, 0x4f7ffffe, v5
	v_cvt_u32_f32_e32 v5, v5
	v_mul_lo_u32 v2, v4, v5
	v_mul_hi_u32 v2, v5, v2
	v_add_u32_e32 v2, v5, v2
	v_mul_hi_u32 v2, v6, v2
	v_mul_lo_u32 v4, v2, v3
	v_sub_u32_e32 v4, v6, v4
	v_add_u32_e32 v5, 1, v2
	v_cmp_ge_u32_e32 vcc, v4, v3
	s_nop 1
	v_cndmask_b32_e32 v2, v2, v5, vcc
	v_sub_u32_e32 v5, v4, v3
	v_cndmask_b32_e32 v4, v4, v5, vcc
	v_add_u32_e32 v5, 1, v2
	v_cmp_ge_u32_e32 vcc, v4, v3
	v_add_u32_e32 v4, 1, v6
	s_nop 0
	v_cndmask_b32_e32 v2, v2, v5, vcc
	v_mul_lo_u32 v5, v3, v2
	v_add_u32_e32 v3, v5, v3
	v_cmp_ne_u32_e32 vcc, v4, v3
	s_and_saveexec_b64 s[6:7], vcc
	s_xor_b64 s[6:7], exec, s[6:7]
	s_cbranch_execz .LBB0_261
	s_waitcnt lgkmcnt(0)
	v_sub_u32_e32 v4, v6, v5
	v_cmp_eq_u32_e32 vcc, 24, v4
	s_cbranch_vccz .Lnf_1
	buffer_wbl2 sc1
.Lnf_1:
	v_mov_b32_e32 v1, 0x3500
	global_load_dword v1, v1, s[30:31] sc1
	s_add_u32 s10, s30, 0x3500
	s_addc_u32 s11, s31, 0
	s_waitcnt vmcnt(0)
	v_cmp_eq_u32_e32 vcc, v1, v2
	s_and_saveexec_b64 s[8:9], vcc
	s_cbranch_execz .LBB0_260
	s_mov_b32 s33, 1
	s_mov_b64 s[12:13], 0
	v_mov_b32_e32 v1, 0
	s_branch .LBB0_251

; __device__ __forceinline__ unsigned xb_ld(unsigned* p)              { return __hip_atomic_load(p, __ATOMIC_RELAXED, __HIP_MEMORY_SCOPE_AGENT); }
; #define XB_SPIN(cond, bar) do { unsigned _sp = 0; while (cond) { __builtin_amdgcn_s_sleep(1); \
;     if ((++_sp & 255u) == 0u) { if (xb_ld(&(bar)[XB_TMO])) break; if (_sp > XB_SPIN_CAP) { atomicAdd(&(bar)[XB_TMO], 1u); break; } } } } while (0)
; __device__ __forceinline__ void xcd_barrier(const XcdBarrier& b) {
;     ...
;         } else {
;             XB_SPIN(xb_ld(&bar[XB_XGEN(b.x)]) == gen, bar);
;             __builtin_amdgcn_fence(__ATOMIC_ACQUIRE, "agent");
;             asm volatile("s_waitcnt vmcnt(0)" ::: "memory");
.Lnf_3:
	v_mov_b32_e32 v1, 0x3500
	global_load_dword v1, v1, s[30:31] sc1
	s_add_u32 s12, s30, 0x3500
	s_addc_u32 s13, s31, 0
	s_waitcnt vmcnt(0)
	v_cmp_eq_u32_e32 vcc, v1, v2
	s_and_saveexec_b64 s[8:9], vcc
	s_cbranch_execz .LBB0_750
	s_mov_b32 s33, 1
	s_mov_b64 s[14:15], 0
	v_mov_b32_e32 v1, 0
	s_branch .LBB0_741

; __device__ __forceinline__ unsigned xb_ld(unsigned* p)              { return __hip_atomic_load(p, __ATOMIC_RELAXED, __HIP_MEMORY_SCOPE_AGENT); }
; #define XB_SPIN(cond, bar) do { unsigned _sp = 0; while (cond) { __builtin_amdgcn_s_sleep(1); \
;     if ((++_sp & 255u) == 0u) { if (xb_ld(&(bar)[XB_TMO])) break; if (_sp > XB_SPIN_CAP) { atomicAdd(&(bar)[XB_TMO], 1u); break; } } } } while (0)
; __device__ __forceinline__ void xcd_barrier(const XcdBarrier& b) {
;     ...
;         } else {
;             XB_SPIN(xb_ld(&bar[XB_XGEN(b.x)]) == gen, bar);
;             __builtin_amdgcn_fence(__ATOMIC_ACQUIRE, "agent");
;             asm volatile("s_waitcnt vmcnt(0)" ::: "memory");
.Lnf_4:
	v_mov_b32_e32 v1, 0x3500
	global_load_dword v1, v1, s[30:31] sc1
	s_add_u32 s10, s30, 0x3500
	s_addc_u32 s11, s31, 0
	s_waitcnt vmcnt(0)
	v_cmp_eq_u32_e32 vcc, v1, v2
	s_and_saveexec_b64 s[8:9], vcc
	s_cbranch_execz .LBB0_833
	s_mov_b32 s24, 1
	s_mov_b64 s[12:13], 0
	v_mov_b32_e32 v1, 0
	s_branch .LBB0_824

; __device__ __forceinline__ unsigned xb_ld(unsigned* p)              { return __hip_atomic_load(p, __ATOMIC_RELAXED, __HIP_MEMORY_SCOPE_AGENT); }
; __device__ __forceinline__ unsigned xb_add(unsigned* p, unsigned v) { return __hip_atomic_fetch_add(p, v, __ATOMIC_RELAXED, __HIP_MEMORY_SCOPE_AGENT); }
; #define XB_SPIN(cond, bar) do { unsigned _sp = 0; while (cond) { __builtin_amdgcn_s_sleep(1); \
;     if ((++_sp & 255u) == 0u) { if (xb_ld(&(bar)[XB_TMO])) break; if (_sp > XB_SPIN_CAP) { atomicAdd(&(bar)[XB_TMO], 1u); break; } } } } while (0)
; __device__ __forceinline__ void xcd_barrier(const XcdBarrier& b) {
;     ...
;         const unsigned old = xb_add(&bar[XB_XSUB(b.x)], 1u);
;         const unsigned gen = old / nloc;
;         if (old + 1u == (gen + 1u) * nloc) {
;             __builtin_amdgcn_fence(__ATOMIC_RELEASE, "agent");
;             asm volatile("s_waitcnt vmcnt(0)" ::: "memory");
;             const unsigned og = xb_add(&bar[XB_TOP], 1u);
;             const unsigned tg = og / nx;
;             if (og + 1u == (tg + 1u) * nx) xb_add(&bar[XB_TOPGEN], 1u);
;             else XB_SPIN(xb_ld(&bar[XB_TOPGEN]) == tg, bar);
;             __builtin_amdgcn_fence(__ATOMIC_ACQUIRE, "agent");
;             xb_add(&bar[XB_XGEN(b.x)], 1u);
;             asm volatile("s_waitcnt vmcnt(0)" ::: "memory");
;         } else {
;             XB_SPIN(xb_ld(&bar[XB_XGEN(b.x)]) == gen, bar);
;             __builtin_amdgcn_fence(__ATOMIC_ACQUIRE, "agent");
;             asm volatile("s_waitcnt vmcnt(0)" ::: "memory");
.LBB0_913:
	s_or_b64 exec, exec, s[14:15]
	v_cvt_f32_u32_e32 v5, v3
	s_waitcnt vmcnt(0)
	v_readfirstlane_b32 s8, v4
	v_sub_u32_e32 v4, 0, v3
	v_rcp_iflag_f32_e32 v5, v5
	v_add_u32_e32 v6, s8, v2
	v_mul_f32_e32 v5, 0x4f7ffffe, v5
	v_cvt_u32_f32_e32 v5, v5
	v_mul_lo_u32 v2, v4, v5
	v_mul_hi_u32 v2, v5, v2
	v_add_u32_e32 v2, v5, v2
	v_mul_hi_u32 v2, v6, v2
	v_mul_lo_u32 v4, v2, v3
	v_sub_u32_e32 v4, v6, v4
	v_add_u32_e32 v5, 1, v2
	v_cmp_ge_u32_e32 vcc, v4, v3
	s_nop 1
	v_cndmask_b32_e32 v2, v2, v5, vcc
	v_sub_u32_e32 v5, v4, v3
	v_cndmask_b32_e32 v4, v4, v5, vcc
	v_add_u32_e32 v5, 1, v2
	v_cmp_ge_u32_e32 vcc, v4, v3
	v_add_u32_e32 v4, 1, v6
	s_nop 0
	v_cndmask_b32_e32 v2, v2, v5, vcc
	v_mul_lo_u32 v5, v3, v2
	v_add_u32_e32 v3, v5, v3
	v_cmp_ne_u32_e32 vcc, v4, v3
	s_and_saveexec_b64 s[8:9], vcc
	s_xor_b64 s[8:9], exec, s[8:9]
	s_cbranch_execz .LBB0_927
	s_waitcnt lgkmcnt(0)
	v_sub_u32_e32 v4, v6, v5
	v_cmp_eq_u32_e32 vcc, 24, v4
	s_cbranch_vccz .Lnf_5
	buffer_wbl2 sc1
.Lnf_5:
	v_mov_b32_e32 v1, 0x3500
	global_load_dword v1, v1, s[30:31] sc1
	s_add_u32 s16, s30, 0x3500
	s_addc_u32 s17, s31, 0
	s_waitcnt vmcnt(0)
	v_cmp_eq_u32_e32 vcc, v1, v2
	s_and_saveexec_b64 s[14:15], vcc
	s_cbranch_execz .LBB0_926
	s_mov_b32 s33, 1
	s_mov_b64 s[20:21], 0
	v_mov_b32_e32 v1, 0
	s_branch .LBB0_917

; __device__ __forceinline__ unsigned xb_ld(unsigned* p)              { return __hip_atomic_load(p, __ATOMIC_RELAXED, __HIP_MEMORY_SCOPE_AGENT); }
; __device__ __forceinline__ unsigned xb_add(unsigned* p, unsigned v) { return __hip_atomic_fetch_add(p, v, __ATOMIC_RELAXED, __HIP_MEMORY_SCOPE_AGENT); }
; #define XB_SPIN(cond, bar) do { unsigned _sp = 0; while (cond) { __builtin_amdgcn_s_sleep(1); \
;     if ((++_sp & 255u) == 0u) { if (xb_ld(&(bar)[XB_TMO])) break; if (_sp > XB_SPIN_CAP) { atomicAdd(&(bar)[XB_TMO], 1u); break; } } } } while (0)
; __device__ __forceinline__ void xcd_barrier(const XcdBarrier& b) {
;     ...
;         const unsigned old = xb_add(&bar[XB_XSUB(b.x)], 1u);
;         const unsigned gen = old / nloc;
;         if (old + 1u == (gen + 1u) * nloc) {
;             __builtin_amdgcn_fence(__ATOMIC_RELEASE, "agent");
;             asm volatile("s_waitcnt vmcnt(0)" ::: "memory");
;             const unsigned og = xb_add(&bar[XB_TOP], 1u);
;             const unsigned tg = og / nx;
;             if (og + 1u == (tg + 1u) * nx) xb_add(&bar[XB_TOPGEN], 1u);
;             else XB_SPIN(xb_ld(&bar[XB_TOPGEN]) == tg, bar);
;             __builtin_amdgcn_fence(__ATOMIC_ACQUIRE, "agent");
;             xb_add(&bar[XB_XGEN(b.x)], 1u);
;             asm volatile("s_waitcnt vmcnt(0)" ::: "memory");
;         } else {
;             XB_SPIN(xb_ld(&bar[XB_XGEN(b.x)]) == gen, bar);
;             __builtin_amdgcn_fence(__ATOMIC_ACQUIRE, "agent");
;             asm volatile("s_waitcnt vmcnt(0)" ::: "memory");
.LBB0_1168:
	s_or_b64 exec, exec, s[6:7]
	v_cvt_f32_u32_e32 v5, v3
	s_waitcnt vmcnt(0)
	v_readfirstlane_b32 s4, v4
	v_sub_u32_e32 v4, 0, v3
	v_rcp_iflag_f32_e32 v5, v5
	v_add_u32_e32 v6, s4, v2
	v_mul_f32_e32 v5, 0x4f7ffffe, v5
	v_cvt_u32_f32_e32 v5, v5
	v_mul_lo_u32 v2, v4, v5
	v_mul_hi_u32 v2, v5, v2
	v_add_u32_e32 v2, v5, v2
	v_mul_hi_u32 v2, v6, v2
	v_mul_lo_u32 v4, v2, v3
	v_sub_u32_e32 v4, v6, v4
	v_add_u32_e32 v5, 1, v2
	v_cmp_ge_u32_e32 vcc, v4, v3
	s_nop 1
	v_cndmask_b32_e32 v2, v2, v5, vcc
	v_sub_u32_e32 v5, v4, v3
	v_cndmask_b32_e32 v4, v4, v5, vcc
	v_add_u32_e32 v5, 1, v2
	v_cmp_ge_u32_e32 vcc, v4, v3
	v_add_u32_e32 v4, 1, v6
	s_nop 0
	v_cndmask_b32_e32 v2, v2, v5, vcc
	v_mul_lo_u32 v5, v3, v2
	v_add_u32_e32 v3, v5, v3
	v_cmp_ne_u32_e32 vcc, v4, v3
	s_and_saveexec_b64 s[4:5], vcc
	s_xor_b64 s[4:5], exec, s[4:5]
	s_cbranch_execz .LBB0_1182
	s_waitcnt lgkmcnt(0)
	v_sub_u32_e32 v4, v6, v5
	v_cmp_eq_u32_e32 vcc, 24, v4
	s_cbranch_vccz .Lnf_8
	buffer_wbl2 sc1
.Lnf_8:
	v_mov_b32_e32 v1, 0x3500
	global_load_dword v1, v1, s[30:31] sc1
	s_add_u32 s8, s30, 0x3500
	s_addc_u32 s9, s31, 0
	s_waitcnt vmcnt(0)
	v_cmp_eq_u32_e32 vcc, v1, v2
	s_and_saveexec_b64 s[6:7], vcc
	s_cbranch_execz .LBB0_1181
	s_mov_b32 s20, 1
	s_mov_b64 s[10:11], 0
	v_mov_b32_e32 v1, 0
	s_branch .LBB0_1172
